# P8-epilogue-second-weight-section-prefetch
# speedup vs baseline: 1.0074x; 1.0013x over previous
;     template <bool EDGE> __device__ __forceinline__ void body(const f32x4 (&acc)[2][2][4][2], const pg8::Unit& u, int wr, int wc, int fr, int fq) const {
;         const int tw0 = 252 * u.pm - 2 + 126 * wr;
;         const int chb = 128 * u.pn + 32 * wc + 8 * fq;
; #pragma unroll
;         for (int n = 0; n < 2; ++n) {
;             const int ch = chb + 4 * n;
;             const f32x4 wv0 = *(const f32x4*)(conv_w + ch), wv1 = *(const f32x4*)(conv_w + NUP + ch), wv2 = *(const f32x4*)(conv_w + 2 * NUP + ch), bv = *(const f32x4*)(conv_b + ch);
;             const f32x4 wg0 = *(const f32x4*)(conv_w + DFF + ch), wg1 = *(const f32x4*)(conv_w + NUP + DFF + ch), wg2 = *(const f32x4*)(conv_w + 2 * NUP + DFF + ch), bg = *(const f32x4*)(conv_b + DFF + ch);
;             const f32x4 v7 = dpp_shr1(acc[1][0][3][n]), v6 = dpp_shr1(acc[1][0][2][n]), g7 = dpp_shr1(acc[1][1][3][n]), g6 = dpp_shr1(acc[1][1][2][n]);
; #pragma unroll
;             for (int k = 0; k < 8; ++k) {
;                 const int ai = k >> 2, m = k & 3, lr = 8 * fr + k, tau = tw0 + lr, sp = tau & 4095;
;                 const f32x4 cv = acc[ai][0][m][n], cg = acc[ai][1][m][n];
;                 const f32x4 p1v = k >= 1 ? acc[(k >= 1 ? k - 1 : 0) >> 2][0][(k >= 1 ? k - 1 : 0) & 3][n] : v7;
;                 const f32x4 p1g = k >= 1 ? acc[(k >= 1 ? k - 1 : 0) >> 2][1][(k >= 1 ? k - 1 : 0) & 3][n] : g7;
;                 const f32x4 p2v = k >= 2 ? acc[(k >= 2 ? k - 2 : 0) >> 2][0][(k >= 2 ? k - 2 : 0) & 3][n] : (k == 1 ? v7 : v6);
;                 const f32x4 p2g = k >= 2 ? acc[(k >= 2 ? k - 2 : 0) >> 2][1][(k >= 2 ? k - 2 : 0) & 3][n] : (k == 1 ? g7 : g6);
;                 f32x4 val, gat;
;                 if (EDGE) { const float m1 = sp >= 1 ? 1.f : 0.f, m2 = sp >= 2 ? 1.f : 0.f;
;                     val = bv + wv2 * cv + (wv1 * m1) * p1v + (wv0 * m2) * p2v; gat = bg + wg2 * cg + (wg1 * m1) * p1g + (wg0 * m2) * p2g; }
;                 else { val = bv + wv2 * cv + wv1 * p1v + wv0 * p2v; gat = bg + wg2 * cg + wg1 * p1g + wg0 * p2g; }
;                 const f32x2 g01 = gelu_pk((f32x2){gat[0], gat[1]}), g23 = gelu_pk((f32x2){gat[2], gat[3]});
;                 u32x2 w; w.x = pk2(g01.x * val[0], g01.y * val[1]); w.y = pk2(g23.x * val[2], g23.y * val[3]);
;                 if (lr >= 2 && tau < NT) *(u32x2*)((char*)hidden + (unsigned)(tau * DFF + ch) * 2u) = w;
.LBB0_787:
	s_or_b64 exec, exec, s[2:3]
	v_or_b32_e32 v220, 4, v164
	v_ashrrev_i32_e32 v221, 31, v220
	v_lshlrev_b64 v[220:221], 2, v[220:221]
	v_lshl_add_u64 v[222:223], s[28:29], 0, v[220:221]
	global_load_dwordx4 v[222:225], v[222:223], off
	v_lshl_add_u64 v[226:227], s[44:45], 0, v[220:221]
	global_load_dwordx4 v[226:229], v[226:227], off
	v_lshl_add_u64 v[230:231], s[46:47], 0, v[220:221]
	global_load_dwordx4 v[230:233], v[230:231], off
	v_lshl_add_u64 v[234:235], s[30:31], 0, v[220:221]
	global_load_dwordx4 v[234:237], v[234:235], off
	v_lshl_add_u64 v[238:239], s[48:49], 0, v[220:221]
	global_load_dwordx4 v[238:241], v[238:239], off
	v_lshl_add_u64 v[242:243], s[50:51], 0, v[220:221]
	global_load_dwordx4 v[242:245], v[242:243], off
	v_lshl_add_u64 v[246:247], s[52:53], 0, v[220:221]
	global_load_dwordx4 v[246:249], v[246:247], off
	v_lshl_add_u64 v[250:251], s[54:55], 0, v[220:221]
	global_load_dwordx4 v[250:253], v[250:251], off
	v_add_u32_e32 v165, s25, v197
	v_cmp_gt_u32_e32 vcc, s59, v165
	s_and_b64 s[2:3], s[6:7], vcc
	v_mul_lo_u32 v182, v165, s73
	s_and_saveexec_b64 s[10:11], s[2:3]
	s_cbranch_execz .LBB0_789
	v_pk_fma_f32 v[180:181], v[116:117], v[152:153], v[156:157]
	v_mov_b64_e32 v[216:217], s[62:63]
	v_pk_fma_f32 v[180:181], v[124:125], v[148:149], v[180:181]
	v_pk_fma_f32 v[178:179], v[118:119], v[154:155], v[158:159]
	v_pk_fma_f32 v[174:175], v[144:145], v[174:175], v[180:181]
	v_pk_fma_f32 v[178:179], v[126:127], v[150:151], v[178:179]
	v_and_b32_e32 v185, 0x7fffffff, v175
	v_and_b32_e32 v184, 0x7fffffff, v174
	v_pk_fma_f32 v[214:215], v[184:185], s[58:59], 1.0 op_sel_hi:[1,0,0]
	v_pk_mul_f32 v[212:213], v[174:175], v[174:175]
	v_rcp_f32_e32 v214, v214
	v_rcp_f32_e32 v215, v215
	v_pk_mul_f32 v[212:213], v[212:213], s[56:57] op_sel_hi:[1,0]
	v_pk_fma_f32 v[176:177], v[146:147], v[176:177], v[178:179]
	v_exp_f32_e32 v212, v212
	v_pk_fma_f32 v[218:219], v[214:215], s[60:61], v[216:217] op_sel_hi:[1,0,0]
	v_exp_f32_e32 v213, v213
	v_pk_fma_f32 v[218:219], v[214:215], v[218:219], s[64:65] op_sel_hi:[1,1,0]
	v_max_f32_e32 v178, 0, v174
	v_pk_fma_f32 v[218:219], v[214:215], v[218:219], s[66:67] op_sel_hi:[1,1,0]
	v_and_b32_e32 v181, 0x7fffffff, v177
	v_pk_fma_f32 v[218:219], v[214:215], v[218:219], s[68:69] op_sel_hi:[1,1,0]
	v_and_b32_e32 v180, 0x7fffffff, v176
	v_pk_mul_f32 v[214:215], v[214:215], v[218:219]
	v_max_f32_e32 v179, 0, v175
	v_pk_mul_f32 v[212:213], v[212:213], v[214:215]
	v_pk_mul_f32 v[188:189], v[176:177], v[176:177]
	v_pk_fma_f32 v[174:175], v[184:185], v[212:213], v[178:179] neg_lo:[1,0,0] neg_hi:[1,0,0]
	v_pk_fma_f32 v[178:179], v[180:181], s[58:59], 1.0 op_sel_hi:[1,0,0]
	v_pk_mul_f32 v[184:185], v[188:189], s[56:57] op_sel_hi:[1,0]
	v_rcp_f32_e32 v178, v178
	v_rcp_f32_e32 v179, v179
	v_exp_f32_e32 v184, v184
	v_exp_f32_e32 v185, v185
	v_pk_fma_f32 v[218:219], v[112:113], v[136:137], v[140:141]
	v_pk_fma_f32 v[188:189], v[178:179], s[60:61], v[216:217] op_sel_hi:[1,0,0]
	v_pk_fma_f32 v[218:219], v[120:121], v[132:133], v[218:219]
	v_pk_fma_f32 v[188:189], v[178:179], v[188:189], s[64:65] op_sel_hi:[1,1,0]
	v_pk_fma_f32 v[214:215], v[114:115], v[138:139], v[142:143]
	v_pk_fma_f32 v[188:189], v[178:179], v[188:189], s[66:67] op_sel_hi:[1,1,0]
	v_pk_fma_f32 v[170:171], v[128:129], v[170:171], v[218:219]
	v_pk_fma_f32 v[188:189], v[178:179], v[188:189], s[68:69] op_sel_hi:[1,1,0]
	v_pk_fma_f32 v[214:215], v[122:123], v[134:135], v[214:215]
	v_pk_mul_f32 v[178:179], v[178:179], v[188:189]
	v_pk_mul_f32 v[170:171], v[170:171], v[174:175]
	v_max_f32_e32 v174, 0, v176
	v_pk_mul_f32 v[178:179], v[184:185], v[178:179]
	v_max_f32_e32 v175, 0, v177
	v_pk_fma_f32 v[172:173], v[130:131], v[172:173], v[214:215]
	v_pk_fma_f32 v[174:175], v[180:181], v[178:179], v[174:175] neg_lo:[1,0,0] neg_hi:[1,0,0]
	v_add_lshl_u32 v165, v182, v164, 1
	v_pk_mul_f32 v[172:173], v[172:173], v[174:175]
	v_cvt_pk_bf16_f32 v170, v170, v171
	v_cvt_pk_bf16_f32 v171, v172, v173
	global_store_dwordx2 v165, v[170:171], s[40:41]

;     template <bool EDGE> __device__ __forceinline__ void body(const f32x4 (&acc)[2][2][4][2], const pg8::Unit& u, int wr, int wc, int fr, int fq) const {
;     ...
;             const int ch = chb + 4 * n;
;             const f32x4 wv0 = *(const f32x4*)(conv_w + ch), wv1 = *(const f32x4*)(conv_w + NUP + ch), wv2 = *(const f32x4*)(conv_w + 2 * NUP + ch), bv = *(const f32x4*)(conv_b + ch);
;             const f32x4 wg0 = *(const f32x4*)(conv_w + DFF + ch), wg1 = *(const f32x4*)(conv_w + NUP + DFF + ch), wg2 = *(const f32x4*)(conv_w + 2 * NUP + DFF + ch), bg = *(const f32x4*)(conv_b + DFF + ch);
;             const f32x4 v7 = dpp_shr1(acc[1][0][3][n]), v6 = dpp_shr1(acc[1][0][2][n]), g7 = dpp_shr1(acc[1][1][3][n]), g6 = dpp_shr1(acc[1][1][2][n]);
.LBB0_801:
	s_or_b64 exec, exec, s[20:21]
	v_or_b32_e32 v164, 4, v164
	v_ashrrev_i32_e32 v165, 31, v164
	s_waitcnt vmcnt(0)
	v_lshlrev_b64 v[156:157], 2, v[164:165]
	v_lshl_add_u64 v[132:133], s[44:45], 0, v[156:157]
	v_lshl_add_u64 v[136:137], s[46:47], 0, v[156:157]
	s_nop 0
	s_nop 0
	s_nop 0
	v_lshl_add_u64 v[144:145], s[48:49], 0, v[156:157]
	v_lshl_add_u64 v[148:149], s[50:51], 0, v[156:157]
	v_lshl_add_u64 v[152:153], s[52:53], 0, v[156:157]
	v_lshl_add_u64 v[156:157], s[54:55], 0, v[156:157]
	s_nop 0
	v_mov_b32_e32 v166, 0
	v_mov_b32_e32 v167, 0
	s_waitcnt vmcnt(0)
	v_mov_b64_e32 v[128:129], v[222:223]
	v_mov_b64_e32 v[130:131], v[224:225]
	v_mov_b64_e32 v[132:133], v[226:227]
	v_mov_b64_e32 v[134:135], v[228:229]
	v_mov_b64_e32 v[136:137], v[230:231]
	v_mov_b64_e32 v[138:139], v[232:233]
	v_mov_b64_e32 v[140:141], v[234:235]
	v_mov_b64_e32 v[142:143], v[236:237]
	v_mov_b64_e32 v[144:145], v[238:239]
	v_mov_b64_e32 v[146:147], v[240:241]
	v_mov_b64_e32 v[148:149], v[242:243]
	v_mov_b64_e32 v[150:151], v[244:245]
	v_mov_b64_e32 v[152:153], v[246:247]
	v_mov_b64_e32 v[154:155], v[248:249]
	v_mov_b64_e32 v[156:157], v[250:251]
	v_mov_b64_e32 v[158:159], v[252:253]
	v_mov_b32_e32 v168, 0
	v_mov_b32_e32 v169, 0
	v_mov_b32_e32 v174, 0
	v_mov_b32_e32 v175, 0
	v_mov_b32_e32 v176, 0
	v_mov_b32_e32 v177, 0
	v_mov_b32_e32 v170, 0
	v_mov_b32_e32 v171, 0
	v_mov_b32_e32 v172, 0
	v_mov_b32_e32 v173, 0
	v_mov_b32_e32 v178, 0
	v_mov_b32_e32 v179, 0
	v_mov_b32_e32 v180, 0
	v_mov_b32_e32 v181, 0
	v_mov_b32_dpp v166, v0 row_shr:1 row_mask:0xf bank_mask:0xf
	v_mov_b32_dpp v167, v1 row_shr:1 row_mask:0xf bank_mask:0xf
	v_mov_b32_dpp v168, v2 row_shr:1 row_mask:0xf bank_mask:0xf
	v_mov_b32_dpp v169, v3 row_shr:1 row_mask:0xf bank_mask:0xf
	v_mov_b32_dpp v174, v4 row_shr:1 row_mask:0xf bank_mask:0xf
	v_mov_b32_dpp v175, v5 row_shr:1 row_mask:0xf bank_mask:0xf
	v_mov_b32_dpp v176, v6 row_shr:1 row_mask:0xf bank_mask:0xf
	v_mov_b32_dpp v177, v7 row_shr:1 row_mask:0xf bank_mask:0xf
	v_mov_b32_dpp v170, v12 row_shr:1 row_mask:0xf bank_mask:0xf
	v_mov_b32_dpp v171, v13 row_shr:1 row_mask:0xf bank_mask:0xf
	v_mov_b32_dpp v172, v14 row_shr:1 row_mask:0xf bank_mask:0xf
	v_mov_b32_dpp v173, v15 row_shr:1 row_mask:0xf bank_mask:0xf
	v_mov_b32_dpp v178, v20 row_shr:1 row_mask:0xf bank_mask:0xf
	v_mov_b32_dpp v179, v21 row_shr:1 row_mask:0xf bank_mask:0xf
	v_mov_b32_dpp v180, v22 row_shr:1 row_mask:0xf bank_mask:0xf
	v_mov_b32_dpp v181, v23 row_shr:1 row_mask:0xf bank_mask:0xf
	s_waitcnt vmcnt(0)
	s_and_saveexec_b64 s[20:21], s[0:1]
	s_cbranch_execnz .LBB0_848
	s_or_b64 exec, exec, s[20:21]
	s_and_saveexec_b64 s[0:1], s[2:3]
	s_cbranch_execnz .LBB0_849

; __device__ __forceinline__ unsigned pk2(float lo, float hi) { const f32x2 v = {lo, hi}; return __builtin_bit_cast(unsigned, __builtin_convertvector(v, bf16x2_hw)); }
;     template <bool EDGE> __device__ __forceinline__ void body(const f32x4 (&acc)[2][2][4][2], const pg8::Unit& u, int wr, int wc, int fr, int fq) const {
;     ...
;             const f32x4 wv0 = *(const f32x4*)(conv_w + ch), wv1 = *(const f32x4*)(conv_w + NUP + ch), wv2 = *(const f32x4*)(conv_w + 2 * NUP + ch), bv = *(const f32x4*)(conv_b + ch);
;             const f32x4 wg0 = *(const f32x4*)(conv_w + DFF + ch), wg1 = *(const f32x4*)(conv_w + NUP + DFF + ch), wg2 = *(const f32x4*)(conv_w + 2 * NUP + DFF + ch), bg = *(const f32x4*)(conv_b + DFF + ch);
;             const f32x4 v7 = dpp_shr1(acc[1][0][3][n]), v6 = dpp_shr1(acc[1][0][2][n]), g7 = dpp_shr1(acc[1][1][3][n]), g6 = dpp_shr1(acc[1][1][2][n]);
; #pragma unroll
;             for (int k = 0; k < 8; ++k) {
;                 const int ai = k >> 2, m = k & 3, lr = 8 * fr + k, tau = tw0 + lr, sp = tau & 4095;
;                 const f32x4 cv = acc[ai][0][m][n], cg = acc[ai][1][m][n];
;                 const f32x4 p1v = k >= 1 ? acc[(k >= 1 ? k - 1 : 0) >> 2][0][(k >= 1 ? k - 1 : 0) & 3][n] : v7;
;                 const f32x4 p1g = k >= 1 ? acc[(k >= 1 ? k - 1 : 0) >> 2][1][(k >= 1 ? k - 1 : 0) & 3][n] : g7;
;                 const f32x4 p2v = k >= 2 ? acc[(k >= 2 ? k - 2 : 0) >> 2][0][(k >= 2 ? k - 2 : 0) & 3][n] : (k == 1 ? v7 : v6);
;                 const f32x4 p2g = k >= 2 ? acc[(k >= 2 ? k - 2 : 0) >> 2][1][(k >= 2 ? k - 2 : 0) & 3][n] : (k == 1 ? g7 : g6);
;                 f32x4 val, gat;
;                 if (EDGE) { const float m1 = sp >= 1 ? 1.f : 0.f, m2 = sp >= 2 ? 1.f : 0.f;
;                     val = bv + wv2 * cv + (wv1 * m1) * p1v + (wv0 * m2) * p2v; gat = bg + wg2 * cg + (wg1 * m1) * p1g + (wg0 * m2) * p2g; }
;                 else { val = bv + wv2 * cv + wv1 * p1v + wv0 * p2v; gat = bg + wg2 * cg + wg1 * p1g + wg0 * p2g; }
;                 const f32x2 g01 = gelu_pk((f32x2){gat[0], gat[1]}), g23 = gelu_pk((f32x2){gat[2], gat[3]});
;                 u32x2 w; w.x = pk2(g01.x * val[0], g01.y * val[1]); w.y = pk2(g23.x * val[2], g23.y * val[3]);
;                 if (lr >= 2 && tau < NT) *(u32x2*)((char*)hidden + (unsigned)(tau * DFF + ch) * 2u) = w;
.LBB0_816:
	s_or_b64 exec, exec, s[10:11]
	v_or_b32_e32 v220, 4, v164
	v_ashrrev_i32_e32 v221, 31, v220
	v_lshlrev_b64 v[220:221], 2, v[220:221]
	v_lshl_add_u64 v[222:223], s[28:29], 0, v[220:221]
	global_load_dwordx4 v[222:225], v[222:223], off
	v_lshl_add_u64 v[226:227], s[44:45], 0, v[220:221]
	global_load_dwordx4 v[226:229], v[226:227], off
	v_lshl_add_u64 v[230:231], s[46:47], 0, v[220:221]
	global_load_dwordx4 v[230:233], v[230:231], off
	v_lshl_add_u64 v[234:235], s[30:31], 0, v[220:221]
	global_load_dwordx4 v[234:237], v[234:235], off
	v_lshl_add_u64 v[238:239], s[48:49], 0, v[220:221]
	global_load_dwordx4 v[238:241], v[238:239], off
	v_lshl_add_u64 v[242:243], s[50:51], 0, v[220:221]
	global_load_dwordx4 v[242:245], v[242:243], off
	v_lshl_add_u64 v[246:247], s[52:53], 0, v[220:221]
	global_load_dwordx4 v[246:249], v[246:247], off
	v_lshl_add_u64 v[250:251], s[54:55], 0, v[220:221]
	global_load_dwordx4 v[250:253], v[250:251], off
	v_add_u32_e32 v171, s25, v198
	v_and_b32_e32 v170, 0xffe, v171
	v_cmp_gt_i32_e32 vcc, s59, v171
	v_mul_lo_u32 v171, v171, s73
	s_and_saveexec_b64 s[12:13], vcc
	s_cbranch_execz .LBB0_818
	v_cmp_eq_u32_e64 s[10:11], 0, v170
	v_pk_fma_f32 v[174:175], v[108:109], v[152:153], v[156:157]
	v_pk_fma_f32 v[172:173], v[110:111], v[154:155], v[158:159]
	v_cndmask_b32_e64 v176, 1.0, 0, s[10:11]
	v_pk_mul_f32 v[182:183], v[176:177], v[148:149] op_sel_hi:[0,1]
	v_pk_mul_f32 v[180:181], v[176:177], v[150:151] op_sel_hi:[0,1]
	v_pk_fma_f32 v[174:175], v[116:117], v[182:183], v[174:175]
	v_pk_mul_f32 v[182:183], v[176:177], v[144:145] op_sel_hi:[0,1]
	v_pk_fma_f32 v[172:173], v[118:119], v[180:181], v[172:173]
	v_pk_mul_f32 v[180:181], v[176:177], v[146:147] op_sel_hi:[0,1]
	v_pk_fma_f32 v[124:125], v[124:125], v[182:183], v[174:175]
	v_pk_fma_f32 v[126:127], v[126:127], v[180:181], v[172:173]
	v_and_b32_e32 v181, 0x7fffffff, v125
	v_and_b32_e32 v180, 0x7fffffff, v124
	v_pk_fma_f32 v[188:189], v[180:181], s[58:59], 1.0 op_sel_hi:[1,0,0]
	v_pk_mul_f32 v[184:185], v[124:125], v[124:125]
	v_rcp_f32_e32 v188, v188
	v_rcp_f32_e32 v189, v189
	v_mov_b64_e32 v[212:213], s[62:63]
	v_pk_mul_f32 v[184:185], v[184:185], s[56:57] op_sel_hi:[1,0]
	v_max_f32_e32 v172, 0, v124
	v_pk_fma_f32 v[214:215], v[188:189], s[60:61], v[212:213] op_sel_hi:[1,0,0]
	v_exp_f32_e32 v184, v184
	v_exp_f32_e32 v185, v185
	v_pk_fma_f32 v[214:215], v[188:189], v[214:215], s[64:65] op_sel_hi:[1,1,0]
	v_and_b32_e32 v175, 0x7fffffff, v127
	v_pk_fma_f32 v[214:215], v[188:189], v[214:215], s[66:67] op_sel_hi:[1,1,0]
	v_and_b32_e32 v174, 0x7fffffff, v126
	v_pk_fma_f32 v[214:215], v[188:189], v[214:215], s[68:69] op_sel_hi:[1,1,0]
	v_max_f32_e32 v173, 0, v125
	v_pk_mul_f32 v[188:189], v[188:189], v[214:215]
	v_pk_fma_f32 v[214:215], v[104:105], v[136:137], v[140:141]
	v_pk_mul_f32 v[184:185], v[184:185], v[188:189]
	v_pk_fma_f32 v[188:189], v[106:107], v[138:139], v[142:143]
	v_pk_fma_f32 v[124:125], v[180:181], v[184:185], v[172:173] neg_lo:[1,0,0] neg_hi:[1,0,0]
	v_pk_fma_f32 v[172:173], v[174:175], s[58:59], 1.0 op_sel_hi:[1,0,0]
	v_pk_mul_f32 v[216:217], v[176:177], v[134:135] op_sel_hi:[0,1]
	v_rcp_f32_e32 v172, v172
	v_rcp_f32_e32 v173, v173
	v_pk_mul_f32 v[218:219], v[176:177], v[132:133] op_sel_hi:[0,1]
	v_pk_mul_f32 v[182:183], v[126:127], v[126:127]
	v_pk_fma_f32 v[188:189], v[114:115], v[216:217], v[188:189]
	v_pk_fma_f32 v[214:215], v[112:113], v[218:219], v[214:215]
	v_pk_mul_f32 v[216:217], v[176:177], v[130:131] op_sel_hi:[0,1]
	v_pk_mul_f32 v[176:177], v[176:177], v[128:129] op_sel_hi:[0,1]
	v_pk_fma_f32 v[120:121], v[120:121], v[176:177], v[214:215]
	v_pk_mul_f32 v[176:177], v[182:183], s[56:57] op_sel_hi:[1,0]
	v_pk_fma_f32 v[180:181], v[172:173], s[60:61], v[212:213] op_sel_hi:[1,0,0]
	v_exp_f32_e32 v176, v176
	v_exp_f32_e32 v177, v177
	v_pk_fma_f32 v[180:181], v[172:173], v[180:181], s[64:65] op_sel_hi:[1,1,0]
	v_pk_mul_f32 v[120:121], v[120:121], v[124:125]
	v_pk_fma_f32 v[180:181], v[172:173], v[180:181], s[66:67] op_sel_hi:[1,1,0]
	v_max_f32_e32 v124, 0, v126
	v_pk_fma_f32 v[180:181], v[172:173], v[180:181], s[68:69] op_sel_hi:[1,1,0]
	v_max_f32_e32 v125, 0, v127
	v_pk_mul_f32 v[172:173], v[172:173], v[180:181]
	v_pk_fma_f32 v[122:123], v[122:123], v[216:217], v[188:189]
	v_pk_mul_f32 v[172:173], v[176:177], v[172:173]
	v_add_lshl_u32 v211, v171, v164, 1
	v_pk_fma_f32 v[124:125], v[174:175], v[172:173], v[124:125] neg_lo:[1,0,0] neg_hi:[1,0,0]
	v_cvt_pk_bf16_f32 v120, v120, v121
	v_pk_mul_f32 v[122:123], v[122:123], v[124:125]
	s_nop 0
	v_cvt_pk_bf16_f32 v121, v122, v123
	global_store_dwordx2 v211, v[120:121], s[40:41]

;     template <bool EDGE> __device__ __forceinline__ void body(const f32x4 (&acc)[2][2][4][2], const pg8::Unit& u, int wr, int wc, int fr, int fq) const {
;     ...
;             const int ch = chb + 4 * n;
;             const f32x4 wv0 = *(const f32x4*)(conv_w + ch), wv1 = *(const f32x4*)(conv_w + NUP + ch), wv2 = *(const f32x4*)(conv_w + 2 * NUP + ch), bv = *(const f32x4*)(conv_b + ch);
;             const f32x4 wg0 = *(const f32x4*)(conv_w + DFF + ch), wg1 = *(const f32x4*)(conv_w + NUP + DFF + ch), wg2 = *(const f32x4*)(conv_w + 2 * NUP + DFF + ch), bg = *(const f32x4*)(conv_b + DFF + ch);
;             const f32x4 v7 = dpp_shr1(acc[1][0][3][n]), v6 = dpp_shr1(acc[1][0][2][n]), g7 = dpp_shr1(acc[1][1][3][n]), g6 = dpp_shr1(acc[1][1][2][n]);
.LBB0_828:
	s_or_b64 exec, exec, s[24:25]
	v_or_b32_e32 v96, 4, v164
	v_ashrrev_i32_e32 v97, 31, v96
	v_lshlrev_b64 v[92:93], 2, v[96:97]
	v_lshl_add_u64 v[68:69], s[44:45], 0, v[92:93]
	v_lshl_add_u64 v[72:73], s[46:47], 0, v[92:93]
	s_nop 0
	s_nop 0
	s_nop 0
	v_lshl_add_u64 v[80:81], s[48:49], 0, v[92:93]
	v_lshl_add_u64 v[84:85], s[50:51], 0, v[92:93]
	v_lshl_add_u64 v[88:89], s[52:53], 0, v[92:93]
	v_lshl_add_u64 v[92:93], s[54:55], 0, v[92:93]
	s_nop 0
	v_mov_b32_e32 v98, 0
	v_mov_b32_e32 v99, 0
	s_waitcnt vmcnt(0)
	v_mov_b64_e32 v[64:65], v[222:223]
	v_mov_b64_e32 v[66:67], v[224:225]
	v_mov_b64_e32 v[68:69], v[226:227]
	v_mov_b64_e32 v[70:71], v[228:229]
	v_mov_b64_e32 v[72:73], v[230:231]
	v_mov_b64_e32 v[74:75], v[232:233]
	v_mov_b64_e32 v[76:77], v[234:235]
	v_mov_b64_e32 v[78:79], v[236:237]
	v_mov_b64_e32 v[80:81], v[238:239]
	v_mov_b64_e32 v[82:83], v[240:241]
	v_mov_b64_e32 v[84:85], v[242:243]
	v_mov_b64_e32 v[86:87], v[244:245]
	v_mov_b64_e32 v[88:89], v[246:247]
	v_mov_b64_e32 v[90:91], v[248:249]
	v_mov_b64_e32 v[92:93], v[250:251]
	v_mov_b64_e32 v[94:95], v[252:253]
	v_mov_b32_e32 v100, 0
	v_mov_b32_e32 v101, 0
	v_mov_b32_e32 v106, 0
	v_mov_b32_e32 v107, 0
	v_mov_b32_e32 v108, 0
	v_mov_b32_e32 v109, 0
	v_mov_b32_e32 v102, 0
	v_mov_b32_e32 v103, 0
	v_mov_b32_e32 v104, 0
	v_mov_b32_e32 v105, 0
	v_mov_b32_e32 v110, 0
	v_mov_b32_e32 v111, 0
	v_mov_b32_e32 v112, 0
	v_mov_b32_e32 v113, 0
	v_mov_b32_dpp v98, v0 row_shr:1 row_mask:0xf bank_mask:0xf
	v_mov_b32_dpp v99, v1 row_shr:1 row_mask:0xf bank_mask:0xf
	v_mov_b32_dpp v100, v2 row_shr:1 row_mask:0xf bank_mask:0xf
	v_mov_b32_dpp v101, v3 row_shr:1 row_mask:0xf bank_mask:0xf
	v_mov_b32_dpp v106, v4 row_shr:1 row_mask:0xf bank_mask:0xf
	v_mov_b32_dpp v107, v5 row_shr:1 row_mask:0xf bank_mask:0xf
	v_mov_b32_dpp v108, v6 row_shr:1 row_mask:0xf bank_mask:0xf
	v_mov_b32_dpp v109, v7 row_shr:1 row_mask:0xf bank_mask:0xf
	v_mov_b32_dpp v102, v12 row_shr:1 row_mask:0xf bank_mask:0xf
	v_mov_b32_dpp v103, v13 row_shr:1 row_mask:0xf bank_mask:0xf
	v_mov_b32_dpp v104, v14 row_shr:1 row_mask:0xf bank_mask:0xf
	v_mov_b32_dpp v105, v15 row_shr:1 row_mask:0xf bank_mask:0xf
	v_mov_b32_dpp v110, v20 row_shr:1 row_mask:0xf bank_mask:0xf
	v_mov_b32_dpp v111, v21 row_shr:1 row_mask:0xf bank_mask:0xf
	v_mov_b32_dpp v112, v22 row_shr:1 row_mask:0xf bank_mask:0xf
	v_mov_b32_dpp v113, v23 row_shr:1 row_mask:0xf bank_mask:0xf
	s_waitcnt vmcnt(0)
	s_and_saveexec_b64 s[24:25], s[0:1]
	s_cbranch_execnz .LBB0_841
	s_or_b64 exec, exec, s[24:25]
	s_and_saveexec_b64 s[0:1], s[2:3]
	s_cbranch_execnz .LBB0_842
